# sc8 + P5 loop: the 14 XNACK s_nop pads between m0 writes and LDS-DMA loads removed
# baseline (speedup 1.0000x reference)
.LBB0_872:
	s_add_i32 s77, s52, 2
	s_add_u32 s50, s34, 0xfffc0080
	s_addc_u32 s51, s35, -1
	s_cmp_eq_u32 s70, s52
	s_cselect_b32 s52, s30, s21
	s_cselect_b32 s55, s29, s51
	s_cselect_b32 s54, s28, s50
	s_cselect_b32 s53, s31, s23
	ds_read_b128 v[150:153], v246
	ds_read_b128 v[154:157], v246 offset:1024
	ds_read_b128 v[158:161], v246 offset:2048
	ds_read_b128 v[162:165], v246 offset:3072
	ds_read_b128 v[166:169], v247
	ds_read_b128 v[170:173], v247 offset:1024
	ds_read_b128 v[174:177], v247 offset:2048
	ds_read_b128 v[178:181], v247 offset:3072
	ds_read_b128 v[182:185], v149
	ds_read_b128 v[186:189], v149 offset:1024
	ds_read_b128 v[190:193], v149 offset:2048
	ds_read_b128 v[194:197], v149 offset:3072
	ds_read_b128 v[198:201], v149 offset:4096
	ds_read_b128 v[202:205], v149 offset:5120
	ds_read_b128 v[206:209], v149 offset:6144
	ds_read_b128 v[210:213], v149 offset:7168
	s_add_i32 m0, s60, 0xc000
	global_load_lds_dwordx4 v132, s[34:35]
	s_add_i32 m0, s60, 0xe000
	global_load_lds_dwordx4 v134, s[34:35]
	s_waitcnt vmcnt(8)
	s_waitcnt lgkmcnt(0)
	s_barrier
	v_mfma_f32_16x16x32_bf16 v[78:81], v[150:153], v[182:185], v[78:81]
	v_mfma_f32_16x16x32_bf16 v[78:81], v[154:157], v[186:189], v[78:81]
	v_mfma_f32_16x16x32_bf16 v[66:69], v[154:157], v[194:197], v[66:69]
	v_mfma_f32_16x16x32_bf16 v[66:69], v[150:153], v[190:193], v[66:69]
	v_mfma_f32_16x16x32_bf16 v[70:73], v[150:153], v[198:201], v[70:73]
	v_mfma_f32_16x16x32_bf16 v[70:73], v[154:157], v[202:205], v[70:73]
	v_mfma_f32_16x16x32_bf16 v[74:77], v[154:157], v[210:213], v[74:77]
	v_mfma_f32_16x16x32_bf16 v[74:77], v[150:153], v[206:209], v[74:77]
	v_mfma_f32_16x16x32_bf16 v[10:13], v[158:161], v[206:209], v[10:13]
	v_mfma_f32_16x16x32_bf16 v[10:13], v[162:165], v[210:213], v[10:13]
	v_mfma_f32_16x16x32_bf16 v[6:9], v[162:165], v[202:205], v[6:9]
	v_mfma_f32_16x16x32_bf16 v[6:9], v[158:161], v[198:201], v[6:9]
	v_mfma_f32_16x16x32_bf16 v[2:5], v[158:161], v[190:193], v[2:5]
	v_mfma_f32_16x16x32_bf16 v[2:5], v[162:165], v[194:197], v[2:5]
	v_mfma_f32_16x16x32_bf16 v[14:17], v[162:165], v[186:189], v[14:17]
	v_mfma_f32_16x16x32_bf16 v[14:17], v[158:161], v[182:185], v[14:17]
	v_mfma_f32_16x16x32_bf16 v[98:101], v[166:169], v[182:185], v[98:101]
	v_mfma_f32_16x16x32_bf16 v[98:101], v[170:173], v[186:189], v[98:101]
	v_mfma_f32_16x16x32_bf16 v[82:85], v[170:173], v[194:197], v[82:85]
	v_mfma_f32_16x16x32_bf16 v[82:85], v[166:169], v[190:193], v[82:85]
	v_mfma_f32_16x16x32_bf16 v[86:89], v[166:169], v[198:201], v[86:89]
	v_mfma_f32_16x16x32_bf16 v[86:89], v[170:173], v[202:205], v[86:89]
	v_mfma_f32_16x16x32_bf16 v[94:97], v[170:173], v[210:213], v[94:97]
	v_mfma_f32_16x16x32_bf16 v[94:97], v[166:169], v[206:209], v[94:97]
	v_mfma_f32_16x16x32_bf16 v[30:33], v[174:177], v[206:209], v[30:33]
	v_mfma_f32_16x16x32_bf16 v[30:33], v[178:181], v[210:213], v[30:33]
	v_mfma_f32_16x16x32_bf16 v[22:25], v[178:181], v[202:205], v[22:25]
	v_mfma_f32_16x16x32_bf16 v[22:25], v[174:177], v[198:201], v[22:25]
	v_mfma_f32_16x16x32_bf16 v[18:21], v[174:177], v[190:193], v[18:21]
	v_mfma_f32_16x16x32_bf16 v[18:21], v[178:181], v[194:197], v[18:21]
	v_mfma_f32_16x16x32_bf16 v[34:37], v[178:181], v[186:189], v[34:37]
	v_mfma_f32_16x16x32_bf16 v[34:37], v[174:177], v[182:185], v[34:37]
	s_barrier
	ds_read_b128 v[182:185], v149 offset:16384
	ds_read_b128 v[186:189], v149 offset:17408
	ds_read_b128 v[190:193], v149 offset:18432
	ds_read_b128 v[194:197], v149 offset:19456
	ds_read_b128 v[198:201], v149 offset:20480
	ds_read_b128 v[202:205], v149 offset:21504
	ds_read_b128 v[206:209], v149 offset:22528
	ds_read_b128 v[210:213], v149 offset:23552
	s_add_i32 s50, s73, s15
	s_mov_b32 m0, s50
	global_load_lds_dwordx4 v228, s[52:53]
	s_add_i32 m0, s50, 0x2000
	s_add_u32 s50, s52, 0x40000
	s_addc_u32 s51, s53, 0
	s_add_i32 s78, s74, s15
	global_load_lds_dwordx4 v232, s[52:53]
	s_mov_b32 m0, s78
	global_load_lds_dwordx4 v228, s[50:51]
	s_add_i32 m0, s78, 0x2000
	global_load_lds_dwordx4 v232, s[50:51]
	s_mov_b32 m0, s60
	global_load_lds_dwordx4 v226, s[54:55]
	s_mov_b32 m0, s61
	global_load_lds_dwordx4 v230, s[54:55]
	s_waitcnt vmcnt(8)
	s_waitcnt lgkmcnt(0)
	s_barrier
	v_mfma_f32_16x16x32_bf16 v[90:93], v[150:153], v[182:185], v[90:93]
	v_mfma_f32_16x16x32_bf16 v[90:93], v[154:157], v[186:189], v[90:93]
	v_mfma_f32_16x16x32_bf16 v[102:105], v[154:157], v[194:197], v[102:105]
	v_mfma_f32_16x16x32_bf16 v[102:105], v[150:153], v[190:193], v[102:105]
	v_mfma_f32_16x16x32_bf16 v[106:109], v[150:153], v[198:201], v[106:109]
	v_mfma_f32_16x16x32_bf16 v[106:109], v[154:157], v[202:205], v[106:109]
	v_mfma_f32_16x16x32_bf16 v[110:113], v[154:157], v[210:213], v[110:113]
	v_mfma_f32_16x16x32_bf16 v[110:113], v[150:153], v[206:209], v[110:113]
	v_mfma_f32_16x16x32_bf16 v[46:49], v[158:161], v[206:209], v[46:49]
	v_mfma_f32_16x16x32_bf16 v[46:49], v[162:165], v[210:213], v[46:49]
	v_mfma_f32_16x16x32_bf16 v[42:45], v[162:165], v[202:205], v[42:45]
	v_mfma_f32_16x16x32_bf16 v[42:45], v[158:161], v[198:201], v[42:45]
	v_mfma_f32_16x16x32_bf16 v[38:41], v[158:161], v[190:193], v[38:41]
	v_mfma_f32_16x16x32_bf16 v[38:41], v[162:165], v[194:197], v[38:41]
	v_mfma_f32_16x16x32_bf16 v[26:29], v[162:165], v[186:189], v[26:29]
	v_mfma_f32_16x16x32_bf16 v[26:29], v[158:161], v[182:185], v[26:29]
	v_mfma_f32_16x16x32_bf16 v[114:117], v[166:169], v[182:185], v[114:117]
	v_mfma_f32_16x16x32_bf16 v[114:117], v[170:173], v[186:189], v[114:117]
	v_mfma_f32_16x16x32_bf16 v[118:121], v[170:173], v[194:197], v[118:121]
	v_mfma_f32_16x16x32_bf16 v[118:121], v[166:169], v[190:193], v[118:121]
	v_mfma_f32_16x16x32_bf16 v[122:125], v[166:169], v[198:201], v[122:125]
	v_mfma_f32_16x16x32_bf16 v[122:125], v[170:173], v[202:205], v[122:125]
	v_mfma_f32_16x16x32_bf16 v[126:129], v[170:173], v[210:213], v[126:129]
	v_mfma_f32_16x16x32_bf16 v[126:129], v[166:169], v[206:209], v[126:129]
	v_mfma_f32_16x16x32_bf16 v[62:65], v[174:177], v[206:209], v[62:65]
	v_mfma_f32_16x16x32_bf16 v[62:65], v[178:181], v[210:213], v[62:65]
	v_mfma_f32_16x16x32_bf16 v[58:61], v[178:181], v[202:205], v[58:61]
	v_mfma_f32_16x16x32_bf16 v[58:61], v[174:177], v[198:201], v[58:61]
	v_mfma_f32_16x16x32_bf16 v[54:57], v[174:177], v[190:193], v[54:57]
	v_mfma_f32_16x16x32_bf16 v[54:57], v[178:181], v[194:197], v[54:57]
	v_mfma_f32_16x16x32_bf16 v[50:53], v[178:181], v[186:189], v[50:53]
	v_mfma_f32_16x16x32_bf16 v[50:53], v[174:177], v[182:185], v[50:53]
	s_barrier
	s_add_i32 s78, 0, 0x18000
	s_add_i32 s79, 0, 0x1c000
	ds_read_b128 v[150:153], v248
	ds_read_b128 v[154:157], v248 offset:1024
	ds_read_b128 v[158:161], v248 offset:2048
	ds_read_b128 v[162:165], v248 offset:3072
	ds_read_b128 v[166:169], v249
	ds_read_b128 v[170:173], v249 offset:1024
	ds_read_b128 v[174:177], v249 offset:2048
	ds_read_b128 v[178:181], v249 offset:3072
	ds_read_b128 v[182:185], v149 offset:32768
	ds_read_b128 v[186:189], v149 offset:33792
	ds_read_b128 v[190:193], v149 offset:34816
	ds_read_b128 v[194:197], v149 offset:35840
	ds_read_b128 v[198:201], v149 offset:36864
	ds_read_b128 v[202:205], v149 offset:37888
	ds_read_b128 v[206:209], v149 offset:38912
	ds_read_b128 v[210:213], v149 offset:39936
	s_add_u32 s50, s54, 0x40000
	s_addc_u32 s51, s55, 0
	s_mov_b32 m0, s62
	global_load_lds_dwordx4 v226, s[50:51]
	s_mov_b32 m0, s63
	global_load_lds_dwordx4 v230, s[50:51]
	s_waitcnt vmcnt(8)
	s_waitcnt lgkmcnt(0)
	s_barrier
	v_mfma_f32_16x16x32_bf16 v[78:81], v[150:153], v[182:185], v[78:81]
	v_mfma_f32_16x16x32_bf16 v[78:81], v[154:157], v[186:189], v[78:81]
	v_mfma_f32_16x16x32_bf16 v[66:69], v[154:157], v[194:197], v[66:69]
	v_mfma_f32_16x16x32_bf16 v[66:69], v[150:153], v[190:193], v[66:69]
	v_mfma_f32_16x16x32_bf16 v[70:73], v[150:153], v[198:201], v[70:73]
	v_mfma_f32_16x16x32_bf16 v[70:73], v[154:157], v[202:205], v[70:73]
	v_mfma_f32_16x16x32_bf16 v[74:77], v[154:157], v[210:213], v[74:77]
	v_mfma_f32_16x16x32_bf16 v[74:77], v[150:153], v[206:209], v[74:77]
	v_mfma_f32_16x16x32_bf16 v[10:13], v[158:161], v[206:209], v[10:13]
	v_mfma_f32_16x16x32_bf16 v[10:13], v[162:165], v[210:213], v[10:13]
	v_mfma_f32_16x16x32_bf16 v[6:9], v[162:165], v[202:205], v[6:9]
	v_mfma_f32_16x16x32_bf16 v[6:9], v[158:161], v[198:201], v[6:9]
	v_mfma_f32_16x16x32_bf16 v[2:5], v[158:161], v[190:193], v[2:5]
	v_mfma_f32_16x16x32_bf16 v[2:5], v[162:165], v[194:197], v[2:5]
	v_mfma_f32_16x16x32_bf16 v[14:17], v[162:165], v[186:189], v[14:17]
	v_mfma_f32_16x16x32_bf16 v[14:17], v[158:161], v[182:185], v[14:17]
	v_mfma_f32_16x16x32_bf16 v[98:101], v[166:169], v[182:185], v[98:101]
	v_mfma_f32_16x16x32_bf16 v[98:101], v[170:173], v[186:189], v[98:101]
	v_mfma_f32_16x16x32_bf16 v[82:85], v[170:173], v[194:197], v[82:85]
	v_mfma_f32_16x16x32_bf16 v[82:85], v[166:169], v[190:193], v[82:85]
	v_mfma_f32_16x16x32_bf16 v[86:89], v[166:169], v[198:201], v[86:89]
	v_mfma_f32_16x16x32_bf16 v[86:89], v[170:173], v[202:205], v[86:89]
	v_mfma_f32_16x16x32_bf16 v[94:97], v[170:173], v[210:213], v[94:97]
	v_mfma_f32_16x16x32_bf16 v[94:97], v[166:169], v[206:209], v[94:97]
	v_mfma_f32_16x16x32_bf16 v[30:33], v[174:177], v[206:209], v[30:33]
	v_mfma_f32_16x16x32_bf16 v[30:33], v[178:181], v[210:213], v[30:33]
	v_mfma_f32_16x16x32_bf16 v[22:25], v[178:181], v[202:205], v[22:25]
	v_mfma_f32_16x16x32_bf16 v[22:25], v[174:177], v[198:201], v[22:25]
	v_mfma_f32_16x16x32_bf16 v[18:21], v[174:177], v[190:193], v[18:21]
	v_mfma_f32_16x16x32_bf16 v[18:21], v[178:181], v[194:197], v[18:21]
	v_mfma_f32_16x16x32_bf16 v[34:37], v[178:181], v[186:189], v[34:37]
	v_mfma_f32_16x16x32_bf16 v[34:37], v[174:177], v[182:185], v[34:37]
	s_barrier
	ds_read_b128 v[182:185], v149 offset:49152
	ds_read_b128 v[186:189], v149 offset:50176
	ds_read_b128 v[190:193], v149 offset:51200
	ds_read_b128 v[194:197], v149 offset:52224
	ds_read_b128 v[198:201], v149 offset:53248
	ds_read_b128 v[202:205], v149 offset:54272
	ds_read_b128 v[206:209], v149 offset:55296
	ds_read_b128 v[210:213], v149 offset:56320
	s_add_u32 s98, s52, 0x80
	s_addc_u32 s99, s53, 0
	s_add_u32 s100, s54, 0x80
	s_addc_u32 s101, s55, 0
	s_add_i32 s50, s78, s15
	s_mov_b32 m0, s50
	global_load_lds_dwordx4 v228, s[98:99]
	s_add_i32 m0, s50, 0x2000
	s_add_u32 s50, s52, 0x40080
	s_addc_u32 s51, s53, 0
	global_load_lds_dwordx4 v232, s[98:99]
	s_add_i32 s52, s79, s15
	s_mov_b32 m0, s52
	global_load_lds_dwordx4 v228, s[50:51]
	s_add_i32 m0, s52, 0x2000
	global_load_lds_dwordx4 v232, s[50:51]
	s_mov_b32 m0, s68
	global_load_lds_dwordx4 v226, s[100:101]
	s_mov_b32 m0, s69
	global_load_lds_dwordx4 v230, s[100:101]
	s_waitcnt vmcnt(8)
	s_waitcnt lgkmcnt(0)
	s_barrier
	v_mfma_f32_16x16x32_bf16 v[90:93], v[150:153], v[182:185], v[90:93]
	v_mfma_f32_16x16x32_bf16 v[90:93], v[154:157], v[186:189], v[90:93]
	v_mfma_f32_16x16x32_bf16 v[102:105], v[154:157], v[194:197], v[102:105]
	v_mfma_f32_16x16x32_bf16 v[102:105], v[150:153], v[190:193], v[102:105]
	v_mfma_f32_16x16x32_bf16 v[106:109], v[150:153], v[198:201], v[106:109]
	v_mfma_f32_16x16x32_bf16 v[106:109], v[154:157], v[202:205], v[106:109]
	v_mfma_f32_16x16x32_bf16 v[110:113], v[154:157], v[210:213], v[110:113]
	v_mfma_f32_16x16x32_bf16 v[110:113], v[150:153], v[206:209], v[110:113]
	v_mfma_f32_16x16x32_bf16 v[46:49], v[158:161], v[206:209], v[46:49]
	v_mfma_f32_16x16x32_bf16 v[46:49], v[162:165], v[210:213], v[46:49]
	v_mfma_f32_16x16x32_bf16 v[42:45], v[162:165], v[202:205], v[42:45]
	v_mfma_f32_16x16x32_bf16 v[42:45], v[158:161], v[198:201], v[42:45]
	v_mfma_f32_16x16x32_bf16 v[38:41], v[158:161], v[190:193], v[38:41]
	v_mfma_f32_16x16x32_bf16 v[38:41], v[162:165], v[194:197], v[38:41]
	v_mfma_f32_16x16x32_bf16 v[26:29], v[162:165], v[186:189], v[26:29]
	v_mfma_f32_16x16x32_bf16 v[26:29], v[158:161], v[182:185], v[26:29]
	v_mfma_f32_16x16x32_bf16 v[114:117], v[166:169], v[182:185], v[114:117]
	v_mfma_f32_16x16x32_bf16 v[114:117], v[170:173], v[186:189], v[114:117]
	v_mfma_f32_16x16x32_bf16 v[118:121], v[170:173], v[194:197], v[118:121]
	v_mfma_f32_16x16x32_bf16 v[118:121], v[166:169], v[190:193], v[118:121]
	v_mfma_f32_16x16x32_bf16 v[122:125], v[166:169], v[198:201], v[122:125]
	v_mfma_f32_16x16x32_bf16 v[122:125], v[170:173], v[202:205], v[122:125]
	v_mfma_f32_16x16x32_bf16 v[126:129], v[170:173], v[210:213], v[126:129]
	v_mfma_f32_16x16x32_bf16 v[126:129], v[166:169], v[206:209], v[126:129]
	v_mfma_f32_16x16x32_bf16 v[62:65], v[174:177], v[206:209], v[62:65]
	v_mfma_f32_16x16x32_bf16 v[62:65], v[178:181], v[210:213], v[62:65]
	v_mfma_f32_16x16x32_bf16 v[58:61], v[178:181], v[202:205], v[58:61]
	v_mfma_f32_16x16x32_bf16 v[58:61], v[174:177], v[198:201], v[58:61]
	v_mfma_f32_16x16x32_bf16 v[54:57], v[174:177], v[190:193], v[54:57]
	v_mfma_f32_16x16x32_bf16 v[54:57], v[178:181], v[194:197], v[54:57]
	v_mfma_f32_16x16x32_bf16 v[50:53], v[178:181], v[186:189], v[50:53]
	v_mfma_f32_16x16x32_bf16 v[50:53], v[174:177], v[182:185], v[50:53]
	s_barrier
	s_add_u32 s34, s34, 0x100
	s_addc_u32 s35, s35, 0
	s_add_u32 s21, s21, 0x100
	s_addc_u32 s23, s23, 0
	s_cmp_ge_i32 s77, s66
	s_mov_b32 s52, s77
	s_cbranch_scc0 .LBB0_872
